# GEMM closing barrier 3 MFMAs before the block end at priority 2 (tail MFMAs cover the barrier release), prio flips kept
# baseline (speedup 1.0000x reference)
; #define PG8_STAGE(bufoff, gbase, voff) do { _Pragma("unroll") for (int _i = 0; _i < 2; ++_i) \
;         __builtin_amdgcn_global_load_lds((const unsigned*)((const char*)(gbase) + (voff)[_i]), (PG8_LAS unsigned*)(lds + (bufoff) + ldsw + _i * 8192), 16, 0, 0); } while (0)
; #define PG8_LDA(dst, b, h) do { _Pragma("unroll") for (int m = 0; m < 4; ++m) _Pragma("unroll") for (int k = 0; k < 2; ++k) dst[m][k] = *(const PG8_LAS bf16x8*)(lds + PG8_SA(b, h) + aoff + m * 2048 + k * 1024); } while (0)
; #define PG8_LDB(dst, b, h) do { _Pragma("unroll") for (int n = 0; n < 2; ++n) _Pragma("unroll") for (int k = 0; k < 2; ++k) dst[n][k] = *(const PG8_LAS bf16x8*)(lds + PG8_SB(b, h) + boff + n * 2048 + k * 1024); } while (0)
; #define PG8_MMA(ai, bj, At, Bt) do { __builtin_amdgcn_s_setprio(1); _Pragma("unroll") for (int m = 0; m < 4; ++m) _Pragma("unroll") for (int n = 0; n < 2; ++n) _Pragma("unroll") for (int k = 0; k < 2; ++k) \
;         acc[ai][bj][m][n] = __builtin_amdgcn_mfma_f32_16x16x32_bf16(Bt[n][k], At[m][k], acc[ai][bj][m][n], 0, 0, 0); __builtin_amdgcn_s_setprio(0); } while (0)
; #define PG8_WAIT_V(n) asm volatile("s_waitcnt vmcnt(" #n ")" ::: "memory")
; #define PG8_WAIT_L(n) asm volatile("s_waitcnt lgkmcnt(" #n ")" ::: "memory")
; #define PG8_BAR __builtin_amdgcn_s_barrier()
; #define PG8_SCHED __builtin_amdgcn_sched_barrier(0)
; template <class Epi, class Sched, bool ALIGN_EPI = false, bool SP2 = false>
; __device__ __forceinline__ void gemm_phase(PG8_LAS unsigned char* lds, const Gemm g, const Sched& S, const Epi& E, const int tid) {
;     ...
;             PG8_LDB(B0, 0, 0); PG8_LDB(B1, 0, 1); PG8_SCHED; PG8_LDA(At, 0, 0); PG8_STAGE(PG8_SA(1, 1), a1 + hstep, voffA);
;             PG8_WAIT_V(8); PG8_WAIT_L(0); PG8_BAR; PG8_MMA(0, 0, At, B0); PG8_MMA(0, 1, At, B1); PG8_BAR; PG8_SCHED;
;             PG8_LDA(At, 0, 1); PG8_STAGE(PG8_SB(0, 0), b2, voffB); PG8_STAGE(PG8_SB(0, 1), b2 + hstep, voffB); PG8_STAGE(PG8_SA(0, 0), a2, voffA);
;             PG8_WAIT_V(8); PG8_WAIT_L(0); PG8_BAR; PG8_MMA(1, 0, At, B0); PG8_MMA(1, 1, At, B1); PG8_BAR; PG8_SCHED;
.LBB0_87:
	s_add_u32 s38, s22, s68
	s_addc_u32 s39, s23, s69
	s_add_u32 s38, s38, 0x100
	s_addc_u32 s39, s39, 0
	s_add_u32 s94, s38, 0x3ff80
	s_addc_u32 s95, s39, 0
	s_add_u32 s50, s89, s68
	s_addc_u32 s51, s90, s69
	s_add_i32 s92, 0, 0x10000
	s_cmpk_eq_i32 s68, 0x700
	s_cselect_b32 s73, s15, s39
	s_cselect_b32 s72, s86, s38
	s_cselect_b32 s71, s87, s51
	s_cselect_b32 s70, s88, s50
	s_add_i32 s38, 0, 0x14000
	ds_read_b128 v[170:173], v150
	ds_read_b128 v[174:177], v150 offset:1024
	ds_read_b128 v[178:181], v150 offset:2048
	ds_read_b128 v[182:185], v150 offset:3072
	ds_read_b128 v[186:189], v150 offset:16384
	ds_read_b128 v[190:193], v150 offset:17408
	ds_read_b128 v[206:209], v150 offset:18432
	ds_read_b128 v[210:213], v150 offset:19456
	s_add_i32 m0, s76, 0xc000
	ds_read_b128 v[214:217], v167
	ds_read_b128 v[218:221], v167 offset:1024
	ds_read_b128 v[222:225], v167 offset:2048
	ds_read_b128 v[226:229], v167 offset:3072
	ds_read_b128 v[230:233], v167 offset:4096
	ds_read_b128 v[234:237], v167 offset:5120
	ds_read_b128 v[238:241], v167 offset:6144
	ds_read_b128 v[242:245], v167 offset:7168
	global_load_lds_dwordx4 v138, s[94:95]
	s_add_i32 m0, s76, 0xe000
	s_nop 0
	global_load_lds_dwordx4 v140, s[94:95]
	s_waitcnt vmcnt(8)
	s_waitcnt lgkmcnt(0)
	s_setprio 1
	s_barrier
	v_mfma_f32_16x16x32_bf16 v[126:129], v[170:173], v[214:217], v[126:129]
	v_mfma_f32_16x16x32_bf16 v[122:125], v[178:181], v[214:217], v[122:125]
	v_mfma_f32_16x16x32_bf16 v[110:113], v[170:173], v[222:225], v[110:113]
	v_mfma_f32_16x16x32_bf16 v[106:109], v[178:181], v[222:225], v[106:109]
	v_mfma_f32_16x16x32_bf16 v[94:97], v[170:173], v[230:233], v[94:97]
	v_mfma_f32_16x16x32_bf16 v[90:93], v[178:181], v[230:233], v[90:93]
	v_mfma_f32_16x16x32_bf16 v[78:81], v[170:173], v[238:241], v[78:81]
	v_mfma_f32_16x16x32_bf16 v[74:77], v[178:181], v[238:241], v[74:77]
	v_mfma_f32_16x16x32_bf16 v[126:129], v[174:177], v[218:221], v[126:129]
	v_mfma_f32_16x16x32_bf16 v[122:125], v[182:185], v[218:221], v[122:125]
	v_mfma_f32_16x16x32_bf16 v[110:113], v[174:177], v[226:229], v[110:113]
	v_mfma_f32_16x16x32_bf16 v[106:109], v[182:185], v[226:229], v[106:109]
	v_mfma_f32_16x16x32_bf16 v[94:97], v[174:177], v[234:237], v[94:97]
	v_mfma_f32_16x16x32_bf16 v[90:93], v[182:185], v[234:237], v[90:93]
	v_mfma_f32_16x16x32_bf16 v[78:81], v[174:177], v[242:245], v[78:81]
	v_mfma_f32_16x16x32_bf16 v[74:77], v[182:185], v[242:245], v[74:77]
	v_mfma_f32_16x16x32_bf16 v[118:121], v[186:189], v[214:217], v[118:121]
	v_mfma_f32_16x16x32_bf16 v[114:117], v[206:209], v[214:217], v[114:117]
	v_mfma_f32_16x16x32_bf16 v[102:105], v[186:189], v[222:225], v[102:105]
	v_mfma_f32_16x16x32_bf16 v[98:101], v[206:209], v[222:225], v[98:101]
	v_mfma_f32_16x16x32_bf16 v[86:89], v[186:189], v[230:233], v[86:89]
	v_mfma_f32_16x16x32_bf16 v[82:85], v[206:209], v[230:233], v[82:85]
	v_mfma_f32_16x16x32_bf16 v[70:73], v[186:189], v[238:241], v[70:73]
	v_mfma_f32_16x16x32_bf16 v[66:69], v[206:209], v[238:241], v[66:69]
	v_mfma_f32_16x16x32_bf16 v[118:121], v[190:193], v[218:221], v[118:121]
	v_mfma_f32_16x16x32_bf16 v[114:117], v[210:213], v[218:221], v[114:117]
	v_mfma_f32_16x16x32_bf16 v[102:105], v[190:193], v[226:229], v[102:105]
	v_mfma_f32_16x16x32_bf16 v[98:101], v[210:213], v[226:229], v[98:101]
	s_setprio 2
	v_mfma_f32_16x16x32_bf16 v[86:89], v[190:193], v[234:237], v[86:89]
	s_barrier
	v_mfma_f32_16x16x32_bf16 v[82:85], v[210:213], v[234:237], v[82:85]
	v_mfma_f32_16x16x32_bf16 v[70:73], v[190:193], v[242:245], v[70:73]
	v_mfma_f32_16x16x32_bf16 v[66:69], v[210:213], v[242:245], v[66:69]
	s_setprio 0
	s_add_i32 s39, s92, s75
	s_mov_b32 m0, s39
	ds_read_b128 v[214:217], v167 offset:16384
	ds_read_b128 v[218:221], v167 offset:17408
	ds_read_b128 v[222:225], v167 offset:18432
	ds_read_b128 v[226:229], v167 offset:19456
	ds_read_b128 v[230:233], v167 offset:20480
	ds_read_b128 v[234:237], v167 offset:21504
	ds_read_b128 v[238:241], v167 offset:22528
	ds_read_b128 v[242:245], v167 offset:23552
	global_load_lds_dwordx4 v0, s[70:71]
	s_add_i32 m0, s39, 0x2000
	s_add_u32 s50, s70, 0x40000
	s_addc_u32 s51, s71, 0
	s_add_i32 s38, s38, s75
	global_load_lds_dwordx4 v130, s[70:71]
	s_mov_b32 m0, s38
	s_nop 0
	global_load_lds_dwordx4 v0, s[50:51]
	s_add_i32 m0, s38, 0x2000
	s_nop 0
	global_load_lds_dwordx4 v130, s[50:51]
	s_mov_b32 m0, s76
	s_nop 0
	global_load_lds_dwordx4 v134, s[72:73]
	s_mov_b32 m0, s77
	s_nop 0
	global_load_lds_dwordx4 v132, s[72:73]
	s_waitcnt vmcnt(8)
	s_waitcnt lgkmcnt(0)
	s_setprio 1
	s_barrier
	v_mfma_f32_16x16x32_bf16 v[62:65], v[170:173], v[214:217], v[62:65]
	v_mfma_f32_16x16x32_bf16 v[58:61], v[178:181], v[214:217], v[58:61]
	v_mfma_f32_16x16x32_bf16 v[46:49], v[170:173], v[222:225], v[46:49]
	v_mfma_f32_16x16x32_bf16 v[42:45], v[178:181], v[222:225], v[42:45]
	v_mfma_f32_16x16x32_bf16 v[30:33], v[170:173], v[230:233], v[30:33]
	v_mfma_f32_16x16x32_bf16 v[26:29], v[178:181], v[230:233], v[26:29]
	v_mfma_f32_16x16x32_bf16 v[14:17], v[170:173], v[238:241], v[14:17]
	v_mfma_f32_16x16x32_bf16 v[10:13], v[178:181], v[238:241], v[10:13]
	v_mfma_f32_16x16x32_bf16 v[62:65], v[174:177], v[218:221], v[62:65]
	v_mfma_f32_16x16x32_bf16 v[58:61], v[182:185], v[218:221], v[58:61]
	v_mfma_f32_16x16x32_bf16 v[46:49], v[174:177], v[226:229], v[46:49]
	v_mfma_f32_16x16x32_bf16 v[42:45], v[182:185], v[226:229], v[42:45]
	v_mfma_f32_16x16x32_bf16 v[30:33], v[174:177], v[234:237], v[30:33]
	v_mfma_f32_16x16x32_bf16 v[26:29], v[182:185], v[234:237], v[26:29]
	v_mfma_f32_16x16x32_bf16 v[14:17], v[174:177], v[242:245], v[14:17]
	v_mfma_f32_16x16x32_bf16 v[10:13], v[182:185], v[242:245], v[10:13]
	v_mfma_f32_16x16x32_bf16 v[54:57], v[186:189], v[214:217], v[54:57]
	v_mfma_f32_16x16x32_bf16 v[50:53], v[206:209], v[214:217], v[50:53]
	v_mfma_f32_16x16x32_bf16 v[38:41], v[186:189], v[222:225], v[38:41]
	v_mfma_f32_16x16x32_bf16 v[34:37], v[206:209], v[222:225], v[34:37]
	v_mfma_f32_16x16x32_bf16 v[22:25], v[186:189], v[230:233], v[22:25]
	v_mfma_f32_16x16x32_bf16 v[18:21], v[206:209], v[230:233], v[18:21]
	v_mfma_f32_16x16x32_bf16 v[6:9], v[186:189], v[238:241], v[6:9]
	v_mfma_f32_16x16x32_bf16 v[2:5], v[206:209], v[238:241], v[2:5]
	v_mfma_f32_16x16x32_bf16 v[54:57], v[190:193], v[218:221], v[54:57]
	v_mfma_f32_16x16x32_bf16 v[50:53], v[210:213], v[218:221], v[50:53]
	v_mfma_f32_16x16x32_bf16 v[38:41], v[190:193], v[226:229], v[38:41]
	v_mfma_f32_16x16x32_bf16 v[34:37], v[210:213], v[226:229], v[34:37]
	s_setprio 2
	v_mfma_f32_16x16x32_bf16 v[22:25], v[190:193], v[234:237], v[22:25]
	s_barrier
; #define PG8_STAGE(bufoff, gbase, voff) do { _Pragma("unroll") for (int _i = 0; _i < 2; ++_i) \
;         __builtin_amdgcn_global_load_lds((const unsigned*)((const char*)(gbase) + (voff)[_i]), (PG8_LAS unsigned*)(lds + (bufoff) + ldsw + _i * 8192), 16, 0, 0); } while (0)
; #define PG8_LDA(dst, b, h) do { _Pragma("unroll") for (int m = 0; m < 4; ++m) _Pragma("unroll") for (int k = 0; k < 2; ++k) dst[m][k] = *(const PG8_LAS bf16x8*)(lds + PG8_SA(b, h) + aoff + m * 2048 + k * 1024); } while (0)
; #define PG8_LDB(dst, b, h) do { _Pragma("unroll") for (int n = 0; n < 2; ++n) _Pragma("unroll") for (int k = 0; k < 2; ++k) dst[n][k] = *(const PG8_LAS bf16x8*)(lds + PG8_SB(b, h) + boff + n * 2048 + k * 1024); } while (0)
; #define PG8_MMA(ai, bj, At, Bt) do { __builtin_amdgcn_s_setprio(1); _Pragma("unroll") for (int m = 0; m < 4; ++m) _Pragma("unroll") for (int n = 0; n < 2; ++n) _Pragma("unroll") for (int k = 0; k < 2; ++k) \
;         acc[ai][bj][m][n] = __builtin_amdgcn_mfma_f32_16x16x32_bf16(Bt[n][k], At[m][k], acc[ai][bj][m][n], 0, 0, 0); __builtin_amdgcn_s_setprio(0); } while (0)
; #define PG8_WAIT_V(n) asm volatile("s_waitcnt vmcnt(" #n ")" ::: "memory")
; #define PG8_WAIT_L(n) asm volatile("s_waitcnt lgkmcnt(" #n ")" ::: "memory")
; #define PG8_BAR __builtin_amdgcn_s_barrier()
; #define PG8_SCHED __builtin_amdgcn_sched_barrier(0)
; template <class Epi, class Sched, bool ALIGN_EPI = false, bool SP2 = false>
; __device__ __forceinline__ void gemm_phase(PG8_LAS unsigned char* lds, const Gemm g, const Sched& S, const Epi& E, const int tid) {
;     ...
;             PG8_WAIT_V(8); PG8_WAIT_L(0); PG8_BAR; PG8_MMA(1, 0, At, B0); PG8_MMA(1, 1, At, B1); PG8_BAR; PG8_SCHED;
;             PG8_LDB(B0, 1, 0); PG8_LDB(B1, 1, 1); PG8_SCHED; PG8_LDA(At, 1, 0); PG8_STAGE(PG8_SA(0, 1), a2 + hstep, voffA);
;             PG8_WAIT_V(8); PG8_WAIT_L(0); PG8_BAR; PG8_MMA(0, 0, At, B0); PG8_MMA(0, 1, At, B1); PG8_BAR; PG8_SCHED;
;             PG8_LDA(At, 1, 1); PG8_STAGE(PG8_SB(1, 0), b3, voffB); PG8_STAGE(PG8_SB(1, 1), b3 + hstep, voffB); PG8_STAGE(PG8_SA(1, 0), a3, voffA);
;             PG8_WAIT_V(8); PG8_WAIT_L(0); PG8_BAR; PG8_MMA(1, 0, At, B0); PG8_MMA(1, 1, At, B1); PG8_BAR; PG8_SCHED;
	v_mfma_f32_16x16x32_bf16 v[18:21], v[210:213], v[234:237], v[18:21]
	v_mfma_f32_16x16x32_bf16 v[6:9], v[190:193], v[242:245], v[6:9]
	v_mfma_f32_16x16x32_bf16 v[2:5], v[210:213], v[242:245], v[2:5]
	s_setprio 0
	s_add_i32 s38, 0, 0x18000
	s_add_i32 s39, 0, 0x1c000
	ds_read_b128 v[170:173], v150 offset:32768
	ds_read_b128 v[174:177], v150 offset:33792
	ds_read_b128 v[178:181], v150 offset:34816
	ds_read_b128 v[182:185], v150 offset:35840
	ds_read_b128 v[186:189], v150 offset:49152
	ds_read_b128 v[190:193], v150 offset:50176
	ds_read_b128 v[206:209], v150 offset:51200
	ds_read_b128 v[210:213], v150 offset:52224
	s_add_u32 s50, s72, 0x40000
	s_addc_u32 s51, s73, 0
	s_mov_b32 m0, s78
	ds_read_b128 v[214:217], v167 offset:32768
	ds_read_b128 v[218:221], v167 offset:33792
	ds_read_b128 v[222:225], v167 offset:34816
	ds_read_b128 v[226:229], v167 offset:35840
	ds_read_b128 v[230:233], v167 offset:36864
	ds_read_b128 v[234:237], v167 offset:37888
	ds_read_b128 v[238:241], v167 offset:38912
	ds_read_b128 v[242:245], v167 offset:39936
	global_load_lds_dwordx4 v134, s[50:51]
	s_mov_b32 m0, s79
	s_nop 0
	global_load_lds_dwordx4 v132, s[50:51]
	s_waitcnt vmcnt(8)
	s_waitcnt lgkmcnt(0)
	s_setprio 1
	s_barrier
	v_mfma_f32_16x16x32_bf16 v[126:129], v[170:173], v[214:217], v[126:129]
	v_mfma_f32_16x16x32_bf16 v[122:125], v[178:181], v[214:217], v[122:125]
	v_mfma_f32_16x16x32_bf16 v[110:113], v[170:173], v[222:225], v[110:113]
	v_mfma_f32_16x16x32_bf16 v[106:109], v[178:181], v[222:225], v[106:109]
	v_mfma_f32_16x16x32_bf16 v[94:97], v[170:173], v[230:233], v[94:97]
	v_mfma_f32_16x16x32_bf16 v[90:93], v[178:181], v[230:233], v[90:93]
	v_mfma_f32_16x16x32_bf16 v[78:81], v[170:173], v[238:241], v[78:81]
	v_mfma_f32_16x16x32_bf16 v[74:77], v[178:181], v[238:241], v[74:77]
	v_mfma_f32_16x16x32_bf16 v[126:129], v[174:177], v[218:221], v[126:129]
	v_mfma_f32_16x16x32_bf16 v[122:125], v[182:185], v[218:221], v[122:125]
	v_mfma_f32_16x16x32_bf16 v[110:113], v[174:177], v[226:229], v[110:113]
	v_mfma_f32_16x16x32_bf16 v[106:109], v[182:185], v[226:229], v[106:109]
	v_mfma_f32_16x16x32_bf16 v[94:97], v[174:177], v[234:237], v[94:97]
	v_mfma_f32_16x16x32_bf16 v[90:93], v[182:185], v[234:237], v[90:93]
	v_mfma_f32_16x16x32_bf16 v[78:81], v[174:177], v[242:245], v[78:81]
	v_mfma_f32_16x16x32_bf16 v[74:77], v[182:185], v[242:245], v[74:77]
	v_mfma_f32_16x16x32_bf16 v[118:121], v[186:189], v[214:217], v[118:121]
	v_mfma_f32_16x16x32_bf16 v[114:117], v[206:209], v[214:217], v[114:117]
	v_mfma_f32_16x16x32_bf16 v[102:105], v[186:189], v[222:225], v[102:105]
	v_mfma_f32_16x16x32_bf16 v[98:101], v[206:209], v[222:225], v[98:101]
	v_mfma_f32_16x16x32_bf16 v[86:89], v[186:189], v[230:233], v[86:89]
	v_mfma_f32_16x16x32_bf16 v[82:85], v[206:209], v[230:233], v[82:85]
	v_mfma_f32_16x16x32_bf16 v[70:73], v[186:189], v[238:241], v[70:73]
	v_mfma_f32_16x16x32_bf16 v[66:69], v[206:209], v[238:241], v[66:69]
	v_mfma_f32_16x16x32_bf16 v[118:121], v[190:193], v[218:221], v[118:121]
	v_mfma_f32_16x16x32_bf16 v[114:117], v[210:213], v[218:221], v[114:117]
	v_mfma_f32_16x16x32_bf16 v[102:105], v[190:193], v[226:229], v[102:105]
	v_mfma_f32_16x16x32_bf16 v[98:101], v[210:213], v[226:229], v[98:101]
	s_setprio 2
	v_mfma_f32_16x16x32_bf16 v[86:89], v[190:193], v[234:237], v[86:89]
	s_barrier
	v_mfma_f32_16x16x32_bf16 v[82:85], v[210:213], v[234:237], v[82:85]
	v_mfma_f32_16x16x32_bf16 v[70:73], v[190:193], v[242:245], v[70:73]
	v_mfma_f32_16x16x32_bf16 v[66:69], v[210:213], v[242:245], v[66:69]
	s_setprio 0
	s_add_i32 s38, s38, s75
	s_add_u32 s94, s70, 0x80
	s_addc_u32 s95, s71, 0
	s_mov_b32 m0, s38
	ds_read_b128 v[214:217], v167 offset:49152
	ds_read_b128 v[218:221], v167 offset:50176
	ds_read_b128 v[222:225], v167 offset:51200
	ds_read_b128 v[226:229], v167 offset:52224
	ds_read_b128 v[230:233], v167 offset:53248
	ds_read_b128 v[234:237], v167 offset:54272
	ds_read_b128 v[238:241], v167 offset:55296
	ds_read_b128 v[242:245], v167 offset:56320
	global_load_lds_dwordx4 v0, s[94:95]
	s_add_i32 m0, s38, 0x2000
	s_add_u32 s50, s70, 0x40080
	s_addc_u32 s51, s71, 0
	s_add_i32 s38, s39, s75
	global_load_lds_dwordx4 v130, s[94:95]
	s_mov_b32 m0, s38
	s_nop 0
	global_load_lds_dwordx4 v0, s[50:51]
	s_add_i32 m0, s38, 0x2000
	s_nop 0
	global_load_lds_dwordx4 v130, s[50:51]
	s_add_u32 s94, s72, 0x80
	s_addc_u32 s95, s73, 0
	s_mov_b32 m0, s80
	s_nop 0
	global_load_lds_dwordx4 v134, s[94:95]
	s_mov_b32 m0, s81
	s_nop 0
	global_load_lds_dwordx4 v132, s[94:95]
	s_waitcnt vmcnt(8)
	s_waitcnt lgkmcnt(0)
	s_setprio 1
	s_barrier
	v_mfma_f32_16x16x32_bf16 v[62:65], v[170:173], v[214:217], v[62:65]
	v_mfma_f32_16x16x32_bf16 v[58:61], v[178:181], v[214:217], v[58:61]
	v_mfma_f32_16x16x32_bf16 v[46:49], v[170:173], v[222:225], v[46:49]
	v_mfma_f32_16x16x32_bf16 v[42:45], v[178:181], v[222:225], v[42:45]
	v_mfma_f32_16x16x32_bf16 v[30:33], v[170:173], v[230:233], v[30:33]
	v_mfma_f32_16x16x32_bf16 v[26:29], v[178:181], v[230:233], v[26:29]
	v_mfma_f32_16x16x32_bf16 v[14:17], v[170:173], v[238:241], v[14:17]
	v_mfma_f32_16x16x32_bf16 v[10:13], v[178:181], v[238:241], v[10:13]
	v_mfma_f32_16x16x32_bf16 v[62:65], v[174:177], v[218:221], v[62:65]
	v_mfma_f32_16x16x32_bf16 v[58:61], v[182:185], v[218:221], v[58:61]
	v_mfma_f32_16x16x32_bf16 v[46:49], v[174:177], v[226:229], v[46:49]
	v_mfma_f32_16x16x32_bf16 v[42:45], v[182:185], v[226:229], v[42:45]
	v_mfma_f32_16x16x32_bf16 v[30:33], v[174:177], v[234:237], v[30:33]
	v_mfma_f32_16x16x32_bf16 v[26:29], v[182:185], v[234:237], v[26:29]
	v_mfma_f32_16x16x32_bf16 v[14:17], v[174:177], v[242:245], v[14:17]
	v_mfma_f32_16x16x32_bf16 v[10:13], v[182:185], v[242:245], v[10:13]
	v_mfma_f32_16x16x32_bf16 v[54:57], v[186:189], v[214:217], v[54:57]
	v_mfma_f32_16x16x32_bf16 v[50:53], v[206:209], v[214:217], v[50:53]
	v_mfma_f32_16x16x32_bf16 v[38:41], v[186:189], v[222:225], v[38:41]
	v_mfma_f32_16x16x32_bf16 v[34:37], v[206:209], v[222:225], v[34:37]
	v_mfma_f32_16x16x32_bf16 v[22:25], v[186:189], v[230:233], v[22:25]
	v_mfma_f32_16x16x32_bf16 v[18:21], v[206:209], v[230:233], v[18:21]
	v_mfma_f32_16x16x32_bf16 v[6:9], v[186:189], v[238:241], v[6:9]
	v_mfma_f32_16x16x32_bf16 v[2:5], v[206:209], v[238:241], v[2:5]
	v_mfma_f32_16x16x32_bf16 v[54:57], v[190:193], v[218:221], v[54:57]
	v_mfma_f32_16x16x32_bf16 v[50:53], v[210:213], v[218:221], v[50:53]
	v_mfma_f32_16x16x32_bf16 v[38:41], v[190:193], v[226:229], v[38:41]
	v_mfma_f32_16x16x32_bf16 v[34:37], v[210:213], v[226:229], v[34:37]
	s_setprio 2
	v_mfma_f32_16x16x32_bf16 v[22:25], v[190:193], v[234:237], v[22:25]
	s_barrier
	v_mfma_f32_16x16x32_bf16 v[18:21], v[210:213], v[234:237], v[18:21]
	v_mfma_f32_16x16x32_bf16 v[6:9], v[190:193], v[242:245], v[6:9]
	v_mfma_f32_16x16x32_bf16 v[2:5], v[210:213], v[242:245], v[2:5]
	s_setprio 0
	s_add_i32 s91, s91, 2
	s_add_u32 s68, s68, 0x100
	s_addc_u32 s69, s69, 0
	s_cmp_gt_u32 s91, 13
	s_cbranch_scc1 .LBB0_90

; #define PG8_STAGE(bufoff, gbase, voff) do { _Pragma("unroll") for (int _i = 0; _i < 2; ++_i) \
;         __builtin_amdgcn_global_load_lds((const unsigned*)((const char*)(gbase) + (voff)[_i]), (PG8_LAS unsigned*)(lds + (bufoff) + ldsw + _i * 8192), 16, 0, 0); } while (0)
; #define PG8_LDA(dst, b, h) do { _Pragma("unroll") for (int m = 0; m < 4; ++m) _Pragma("unroll") for (int k = 0; k < 2; ++k) dst[m][k] = *(const PG8_LAS bf16x8*)(lds + PG8_SA(b, h) + aoff + m * 2048 + k * 1024); } while (0)
; #define PG8_LDB(dst, b, h) do { _Pragma("unroll") for (int n = 0; n < 2; ++n) _Pragma("unroll") for (int k = 0; k < 2; ++k) dst[n][k] = *(const PG8_LAS bf16x8*)(lds + PG8_SB(b, h) + boff + n * 2048 + k * 1024); } while (0)
; #define PG8_MMA(ai, bj, At, Bt) do { __builtin_amdgcn_s_setprio(1); _Pragma("unroll") for (int m = 0; m < 4; ++m) _Pragma("unroll") for (int n = 0; n < 2; ++n) _Pragma("unroll") for (int k = 0; k < 2; ++k) \
;         acc[ai][bj][m][n] = __builtin_amdgcn_mfma_f32_16x16x32_bf16(Bt[n][k], At[m][k], acc[ai][bj][m][n], 0, 0, 0); __builtin_amdgcn_s_setprio(0); } while (0)
; #define PG8_WAIT_V(n) asm volatile("s_waitcnt vmcnt(" #n ")" ::: "memory")
; #define PG8_WAIT_L(n) asm volatile("s_waitcnt lgkmcnt(" #n ")" ::: "memory")
; #define PG8_BAR __builtin_amdgcn_s_barrier()
; #define PG8_SCHED __builtin_amdgcn_sched_barrier(0)
; template <class Epi, class Sched, bool ALIGN_EPI = false, bool SP2 = false>
; __device__ __forceinline__ void gemm_phase(PG8_LAS unsigned char* lds, const Gemm g, const Sched& S, const Epi& E, const int tid) {
;     ...
;             PG8_LDB(B0, 0, 0); PG8_LDB(B1, 0, 1); PG8_SCHED; PG8_LDA(At, 0, 0); PG8_STAGE(PG8_SA(1, 1), a1 + hstep, voffA);
;             PG8_WAIT_V(8); PG8_WAIT_L(0); PG8_BAR; PG8_MMA(0, 0, At, B0); PG8_MMA(0, 1, At, B1); PG8_BAR; PG8_SCHED;
;             PG8_LDA(At, 0, 1); PG8_STAGE(PG8_SB(0, 0), b2, voffB); PG8_STAGE(PG8_SB(0, 1), b2 + hstep, voffB); PG8_STAGE(PG8_SA(0, 0), a2, voffA);
;             PG8_WAIT_V(8); PG8_WAIT_L(0); PG8_BAR; PG8_MMA(1, 0, At, B0); PG8_MMA(1, 1, At, B1); PG8_BAR; PG8_SCHED;
.LBB0_208:
	s_add_u32 s38, s10, s12
	s_addc_u32 s39, s11, s13
	s_add_u32 s38, s38, 0x100
	s_addc_u32 s39, s39, 0
	s_add_u32 s51, vcc_lo, s12
	s_addc_u32 s74, vcc_hi, s13
	s_add_i32 s59, 0, 0x10000
	s_cmpk_eq_i32 s12, 0x700
	s_cselect_b32 s77, s49, s39
	s_cselect_b32 s76, s78, s38
	s_cselect_b32 s75, s69, s74
	s_cselect_b32 s74, s79, s51
	s_add_i32 s51, 0, 0x14000
	ds_read_b128 v[170:173], v0
	ds_read_b128 v[174:177], v0 offset:1024
	ds_read_b128 v[178:181], v0 offset:2048
	ds_read_b128 v[182:185], v0 offset:3072
	ds_read_b128 v[186:189], v0 offset:16384
	ds_read_b128 v[190:193], v0 offset:17408
	ds_read_b128 v[206:209], v0 offset:18432
	ds_read_b128 v[210:213], v0 offset:19456
	s_add_i32 m0, s84, 0xc000
	ds_read_b128 v[214:217], v167
	ds_read_b128 v[218:221], v167 offset:1024
	ds_read_b128 v[222:225], v167 offset:2048
	ds_read_b128 v[226:229], v167 offset:3072
	ds_read_b128 v[230:233], v167 offset:4096
	ds_read_b128 v[234:237], v167 offset:5120
	ds_read_b128 v[238:241], v167 offset:6144
	ds_read_b128 v[242:245], v167 offset:7168
	global_load_lds_dwordx4 v148, s[38:39]
	s_add_i32 m0, s84, 0xe000
	s_nop 0
	global_load_lds_dwordx4 v150, s[38:39]
	s_waitcnt vmcnt(8)
	s_waitcnt lgkmcnt(0)
	s_setprio 1
	s_barrier
	v_mfma_f32_16x16x32_bf16 v[126:129], v[170:173], v[214:217], v[126:129]
	v_mfma_f32_16x16x32_bf16 v[122:125], v[178:181], v[214:217], v[122:125]
	v_mfma_f32_16x16x32_bf16 v[110:113], v[170:173], v[222:225], v[110:113]
	v_mfma_f32_16x16x32_bf16 v[106:109], v[178:181], v[222:225], v[106:109]
	v_mfma_f32_16x16x32_bf16 v[94:97], v[170:173], v[230:233], v[94:97]
	v_mfma_f32_16x16x32_bf16 v[90:93], v[178:181], v[230:233], v[90:93]
	v_mfma_f32_16x16x32_bf16 v[78:81], v[170:173], v[238:241], v[78:81]
	v_mfma_f32_16x16x32_bf16 v[74:77], v[178:181], v[238:241], v[74:77]
	v_mfma_f32_16x16x32_bf16 v[126:129], v[174:177], v[218:221], v[126:129]
	v_mfma_f32_16x16x32_bf16 v[122:125], v[182:185], v[218:221], v[122:125]
	v_mfma_f32_16x16x32_bf16 v[110:113], v[174:177], v[226:229], v[110:113]
	v_mfma_f32_16x16x32_bf16 v[106:109], v[182:185], v[226:229], v[106:109]
	v_mfma_f32_16x16x32_bf16 v[94:97], v[174:177], v[234:237], v[94:97]
	v_mfma_f32_16x16x32_bf16 v[90:93], v[182:185], v[234:237], v[90:93]
	v_mfma_f32_16x16x32_bf16 v[78:81], v[174:177], v[242:245], v[78:81]
	v_mfma_f32_16x16x32_bf16 v[74:77], v[182:185], v[242:245], v[74:77]
	v_mfma_f32_16x16x32_bf16 v[118:121], v[186:189], v[214:217], v[118:121]
	v_mfma_f32_16x16x32_bf16 v[114:117], v[206:209], v[214:217], v[114:117]
	v_mfma_f32_16x16x32_bf16 v[102:105], v[186:189], v[222:225], v[102:105]
	v_mfma_f32_16x16x32_bf16 v[98:101], v[206:209], v[222:225], v[98:101]
	v_mfma_f32_16x16x32_bf16 v[86:89], v[186:189], v[230:233], v[86:89]
	v_mfma_f32_16x16x32_bf16 v[82:85], v[206:209], v[230:233], v[82:85]
	v_mfma_f32_16x16x32_bf16 v[70:73], v[186:189], v[238:241], v[70:73]
	v_mfma_f32_16x16x32_bf16 v[66:69], v[206:209], v[238:241], v[66:69]
	v_mfma_f32_16x16x32_bf16 v[118:121], v[190:193], v[218:221], v[118:121]
	v_mfma_f32_16x16x32_bf16 v[114:117], v[210:213], v[218:221], v[114:117]
	v_mfma_f32_16x16x32_bf16 v[102:105], v[190:193], v[226:229], v[102:105]
	v_mfma_f32_16x16x32_bf16 v[98:101], v[210:213], v[226:229], v[98:101]
	s_setprio 2
	v_mfma_f32_16x16x32_bf16 v[86:89], v[190:193], v[234:237], v[86:89]
	s_barrier
	v_mfma_f32_16x16x32_bf16 v[82:85], v[210:213], v[234:237], v[82:85]
	v_mfma_f32_16x16x32_bf16 v[70:73], v[190:193], v[242:245], v[70:73]
	v_mfma_f32_16x16x32_bf16 v[66:69], v[210:213], v[242:245], v[66:69]
	s_setprio 0
	s_add_i32 s38, s59, s83
	s_mov_b32 m0, s38
	ds_read_b128 v[214:217], v167 offset:16384
	ds_read_b128 v[218:221], v167 offset:17408
	ds_read_b128 v[222:225], v167 offset:18432
	ds_read_b128 v[226:229], v167 offset:19456
	ds_read_b128 v[230:233], v167 offset:20480
	ds_read_b128 v[234:237], v167 offset:21504
	ds_read_b128 v[238:241], v167 offset:22528
	ds_read_b128 v[242:245], v167 offset:23552
	global_load_lds_dwordx4 v134, s[74:75]
	s_add_i32 m0, s38, 0x2000
	s_add_u32 s38, s74, 0x40000
	s_addc_u32 s39, s75, 0
	s_add_i32 s51, s51, s83
	global_load_lds_dwordx4 v130, s[74:75]
	s_mov_b32 m0, s51
	s_nop 0
	global_load_lds_dwordx4 v134, s[38:39]
	s_add_i32 m0, s51, 0x2000
	s_nop 0
	global_load_lds_dwordx4 v130, s[38:39]
	s_mov_b32 m0, s84
	s_nop 0
	global_load_lds_dwordx4 v136, s[76:77]
	s_mov_b32 m0, s85
	s_nop 0
	global_load_lds_dwordx4 v132, s[76:77]
	s_waitcnt vmcnt(8)
	s_waitcnt lgkmcnt(0)
	s_setprio 1
	s_barrier
	v_mfma_f32_16x16x32_bf16 v[62:65], v[170:173], v[214:217], v[62:65]
	v_mfma_f32_16x16x32_bf16 v[58:61], v[178:181], v[214:217], v[58:61]
	v_mfma_f32_16x16x32_bf16 v[46:49], v[170:173], v[222:225], v[46:49]
	v_mfma_f32_16x16x32_bf16 v[42:45], v[178:181], v[222:225], v[42:45]
	v_mfma_f32_16x16x32_bf16 v[30:33], v[170:173], v[230:233], v[30:33]
	v_mfma_f32_16x16x32_bf16 v[26:29], v[178:181], v[230:233], v[26:29]
	v_mfma_f32_16x16x32_bf16 v[14:17], v[170:173], v[238:241], v[14:17]
	v_mfma_f32_16x16x32_bf16 v[10:13], v[178:181], v[238:241], v[10:13]
	v_mfma_f32_16x16x32_bf16 v[62:65], v[174:177], v[218:221], v[62:65]
	v_mfma_f32_16x16x32_bf16 v[58:61], v[182:185], v[218:221], v[58:61]
	v_mfma_f32_16x16x32_bf16 v[46:49], v[174:177], v[226:229], v[46:49]
	v_mfma_f32_16x16x32_bf16 v[42:45], v[182:185], v[226:229], v[42:45]
	v_mfma_f32_16x16x32_bf16 v[30:33], v[174:177], v[234:237], v[30:33]
	v_mfma_f32_16x16x32_bf16 v[26:29], v[182:185], v[234:237], v[26:29]
	v_mfma_f32_16x16x32_bf16 v[14:17], v[174:177], v[242:245], v[14:17]
	v_mfma_f32_16x16x32_bf16 v[10:13], v[182:185], v[242:245], v[10:13]
	v_mfma_f32_16x16x32_bf16 v[54:57], v[186:189], v[214:217], v[54:57]
	v_mfma_f32_16x16x32_bf16 v[50:53], v[206:209], v[214:217], v[50:53]
	v_mfma_f32_16x16x32_bf16 v[38:41], v[186:189], v[222:225], v[38:41]
	v_mfma_f32_16x16x32_bf16 v[34:37], v[206:209], v[222:225], v[34:37]
	v_mfma_f32_16x16x32_bf16 v[22:25], v[186:189], v[230:233], v[22:25]
	v_mfma_f32_16x16x32_bf16 v[18:21], v[206:209], v[230:233], v[18:21]
	v_mfma_f32_16x16x32_bf16 v[6:9], v[186:189], v[238:241], v[6:9]
	v_mfma_f32_16x16x32_bf16 v[2:5], v[206:209], v[238:241], v[2:5]
	v_mfma_f32_16x16x32_bf16 v[54:57], v[190:193], v[218:221], v[54:57]
	v_mfma_f32_16x16x32_bf16 v[50:53], v[210:213], v[218:221], v[50:53]
	v_mfma_f32_16x16x32_bf16 v[38:41], v[190:193], v[226:229], v[38:41]
	v_mfma_f32_16x16x32_bf16 v[34:37], v[210:213], v[226:229], v[34:37]
	s_setprio 2
	v_mfma_f32_16x16x32_bf16 v[22:25], v[190:193], v[234:237], v[22:25]
	s_barrier
; #define PG8_STAGE(bufoff, gbase, voff) do { _Pragma("unroll") for (int _i = 0; _i < 2; ++_i) \
;         __builtin_amdgcn_global_load_lds((const unsigned*)((const char*)(gbase) + (voff)[_i]), (PG8_LAS unsigned*)(lds + (bufoff) + ldsw + _i * 8192), 16, 0, 0); } while (0)
; #define PG8_LDA(dst, b, h) do { _Pragma("unroll") for (int m = 0; m < 4; ++m) _Pragma("unroll") for (int k = 0; k < 2; ++k) dst[m][k] = *(const PG8_LAS bf16x8*)(lds + PG8_SA(b, h) + aoff + m * 2048 + k * 1024); } while (0)
; #define PG8_LDB(dst, b, h) do { _Pragma("unroll") for (int n = 0; n < 2; ++n) _Pragma("unroll") for (int k = 0; k < 2; ++k) dst[n][k] = *(const PG8_LAS bf16x8*)(lds + PG8_SB(b, h) + boff + n * 2048 + k * 1024); } while (0)
; #define PG8_MMA(ai, bj, At, Bt) do { __builtin_amdgcn_s_setprio(1); _Pragma("unroll") for (int m = 0; m < 4; ++m) _Pragma("unroll") for (int n = 0; n < 2; ++n) _Pragma("unroll") for (int k = 0; k < 2; ++k) \
;         acc[ai][bj][m][n] = __builtin_amdgcn_mfma_f32_16x16x32_bf16(Bt[n][k], At[m][k], acc[ai][bj][m][n], 0, 0, 0); __builtin_amdgcn_s_setprio(0); } while (0)
; #define PG8_WAIT_V(n) asm volatile("s_waitcnt vmcnt(" #n ")" ::: "memory")
; #define PG8_WAIT_L(n) asm volatile("s_waitcnt lgkmcnt(" #n ")" ::: "memory")
; #define PG8_BAR __builtin_amdgcn_s_barrier()
; #define PG8_SCHED __builtin_amdgcn_sched_barrier(0)
; template <class Epi, class Sched, bool ALIGN_EPI = false, bool SP2 = false>
; __device__ __forceinline__ void gemm_phase(PG8_LAS unsigned char* lds, const Gemm g, const Sched& S, const Epi& E, const int tid) {
;     ...
;             PG8_WAIT_V(8); PG8_WAIT_L(0); PG8_BAR; PG8_MMA(1, 0, At, B0); PG8_MMA(1, 1, At, B1); PG8_BAR; PG8_SCHED;
;             PG8_LDB(B0, 1, 0); PG8_LDB(B1, 1, 1); PG8_SCHED; PG8_LDA(At, 1, 0); PG8_STAGE(PG8_SA(0, 1), a2 + hstep, voffA);
;             PG8_WAIT_V(8); PG8_WAIT_L(0); PG8_BAR; PG8_MMA(0, 0, At, B0); PG8_MMA(0, 1, At, B1); PG8_BAR; PG8_SCHED;
;             PG8_LDA(At, 1, 1); PG8_STAGE(PG8_SB(1, 0), b3, voffB); PG8_STAGE(PG8_SB(1, 1), b3 + hstep, voffB); PG8_STAGE(PG8_SA(1, 0), a3, voffA);
;             PG8_WAIT_V(8); PG8_WAIT_L(0); PG8_BAR; PG8_MMA(1, 0, At, B0); PG8_MMA(1, 1, At, B1); PG8_BAR; PG8_SCHED;
	v_mfma_f32_16x16x32_bf16 v[18:21], v[210:213], v[234:237], v[18:21]
	v_mfma_f32_16x16x32_bf16 v[6:9], v[190:193], v[242:245], v[6:9]
	v_mfma_f32_16x16x32_bf16 v[2:5], v[210:213], v[242:245], v[2:5]
	s_setprio 0
	s_add_i32 s51, 0, 0x18000
	s_add_i32 s59, 0, 0x1c000
	ds_read_b128 v[170:173], v0 offset:32768
	ds_read_b128 v[174:177], v0 offset:33792
	ds_read_b128 v[178:181], v0 offset:34816
	ds_read_b128 v[182:185], v0 offset:35840
	ds_read_b128 v[186:189], v0 offset:49152
	ds_read_b128 v[190:193], v0 offset:50176
	ds_read_b128 v[206:209], v0 offset:51200
	ds_read_b128 v[210:213], v0 offset:52224
	s_add_u32 s38, s76, 0x40000
	s_addc_u32 s39, s77, 0
	s_mov_b32 m0, s86
	ds_read_b128 v[214:217], v167 offset:32768
	ds_read_b128 v[218:221], v167 offset:33792
	ds_read_b128 v[222:225], v167 offset:34816
	ds_read_b128 v[226:229], v167 offset:35840
	ds_read_b128 v[230:233], v167 offset:36864
	ds_read_b128 v[234:237], v167 offset:37888
	ds_read_b128 v[238:241], v167 offset:38912
	ds_read_b128 v[242:245], v167 offset:39936
	global_load_lds_dwordx4 v136, s[38:39]
	s_mov_b32 m0, s87
	s_nop 0
	global_load_lds_dwordx4 v132, s[38:39]
	s_waitcnt vmcnt(8)
	s_waitcnt lgkmcnt(0)
	s_setprio 1
	s_barrier
	v_mfma_f32_16x16x32_bf16 v[126:129], v[170:173], v[214:217], v[126:129]
	v_mfma_f32_16x16x32_bf16 v[122:125], v[178:181], v[214:217], v[122:125]
	v_mfma_f32_16x16x32_bf16 v[110:113], v[170:173], v[222:225], v[110:113]
	v_mfma_f32_16x16x32_bf16 v[106:109], v[178:181], v[222:225], v[106:109]
	v_mfma_f32_16x16x32_bf16 v[94:97], v[170:173], v[230:233], v[94:97]
	v_mfma_f32_16x16x32_bf16 v[90:93], v[178:181], v[230:233], v[90:93]
	v_mfma_f32_16x16x32_bf16 v[78:81], v[170:173], v[238:241], v[78:81]
	v_mfma_f32_16x16x32_bf16 v[74:77], v[178:181], v[238:241], v[74:77]
	v_mfma_f32_16x16x32_bf16 v[126:129], v[174:177], v[218:221], v[126:129]
	v_mfma_f32_16x16x32_bf16 v[122:125], v[182:185], v[218:221], v[122:125]
	v_mfma_f32_16x16x32_bf16 v[110:113], v[174:177], v[226:229], v[110:113]
	v_mfma_f32_16x16x32_bf16 v[106:109], v[182:185], v[226:229], v[106:109]
	v_mfma_f32_16x16x32_bf16 v[94:97], v[174:177], v[234:237], v[94:97]
	v_mfma_f32_16x16x32_bf16 v[90:93], v[182:185], v[234:237], v[90:93]
	v_mfma_f32_16x16x32_bf16 v[78:81], v[174:177], v[242:245], v[78:81]
	v_mfma_f32_16x16x32_bf16 v[74:77], v[182:185], v[242:245], v[74:77]
	v_mfma_f32_16x16x32_bf16 v[118:121], v[186:189], v[214:217], v[118:121]
	v_mfma_f32_16x16x32_bf16 v[114:117], v[206:209], v[214:217], v[114:117]
	v_mfma_f32_16x16x32_bf16 v[102:105], v[186:189], v[222:225], v[102:105]
	v_mfma_f32_16x16x32_bf16 v[98:101], v[206:209], v[222:225], v[98:101]
	v_mfma_f32_16x16x32_bf16 v[86:89], v[186:189], v[230:233], v[86:89]
	v_mfma_f32_16x16x32_bf16 v[82:85], v[206:209], v[230:233], v[82:85]
	v_mfma_f32_16x16x32_bf16 v[70:73], v[186:189], v[238:241], v[70:73]
	v_mfma_f32_16x16x32_bf16 v[66:69], v[206:209], v[238:241], v[66:69]
	v_mfma_f32_16x16x32_bf16 v[118:121], v[190:193], v[218:221], v[118:121]
	v_mfma_f32_16x16x32_bf16 v[114:117], v[210:213], v[218:221], v[114:117]
	v_mfma_f32_16x16x32_bf16 v[102:105], v[190:193], v[226:229], v[102:105]
	v_mfma_f32_16x16x32_bf16 v[98:101], v[210:213], v[226:229], v[98:101]
	s_setprio 2
	v_mfma_f32_16x16x32_bf16 v[86:89], v[190:193], v[234:237], v[86:89]
	s_barrier
	v_mfma_f32_16x16x32_bf16 v[82:85], v[210:213], v[234:237], v[82:85]
	v_mfma_f32_16x16x32_bf16 v[70:73], v[190:193], v[242:245], v[70:73]
	v_mfma_f32_16x16x32_bf16 v[66:69], v[210:213], v[242:245], v[66:69]
	s_setprio 0
	s_add_i32 s38, s51, s83
	s_add_i32 m0, s38, 0xffffff80
	ds_read_b128 v[214:217], v167 offset:49152
	ds_read_b128 v[218:221], v167 offset:50176
	ds_read_b128 v[222:225], v167 offset:51200
	ds_read_b128 v[226:229], v167 offset:52224
	ds_read_b128 v[230:233], v167 offset:53248
	ds_read_b128 v[234:237], v167 offset:54272
	ds_read_b128 v[238:241], v167 offset:55296
	ds_read_b128 v[242:245], v167 offset:56320
	global_load_lds_dwordx4 v134, s[74:75] offset:128
	s_add_i32 m0, s38, 0x1f80
	s_add_u32 s38, s74, 0x40080
	s_addc_u32 s39, s75, 0
	s_add_i32 s51, s59, s83
	global_load_lds_dwordx4 v130, s[74:75] offset:128
	s_mov_b32 m0, s51
	s_nop 0
	global_load_lds_dwordx4 v134, s[38:39]
	s_add_i32 m0, s51, 0x2000
	s_nop 0
	global_load_lds_dwordx4 v130, s[38:39]
	s_add_i32 m0, s88, 0xffffff80
	s_nop 0
	global_load_lds_dwordx4 v136, s[76:77] offset:128
	s_add_i32 m0, s89, 0xffffff80
	s_nop 0
	global_load_lds_dwordx4 v132, s[76:77] offset:128
	s_waitcnt vmcnt(8)
	s_waitcnt lgkmcnt(0)
	s_setprio 1
	s_barrier
	v_mfma_f32_16x16x32_bf16 v[62:65], v[170:173], v[214:217], v[62:65]
	v_mfma_f32_16x16x32_bf16 v[58:61], v[178:181], v[214:217], v[58:61]
	v_mfma_f32_16x16x32_bf16 v[46:49], v[170:173], v[222:225], v[46:49]
	v_mfma_f32_16x16x32_bf16 v[42:45], v[178:181], v[222:225], v[42:45]
	v_mfma_f32_16x16x32_bf16 v[30:33], v[170:173], v[230:233], v[30:33]
	v_mfma_f32_16x16x32_bf16 v[26:29], v[178:181], v[230:233], v[26:29]
	v_mfma_f32_16x16x32_bf16 v[14:17], v[170:173], v[238:241], v[14:17]
	v_mfma_f32_16x16x32_bf16 v[10:13], v[178:181], v[238:241], v[10:13]
	v_mfma_f32_16x16x32_bf16 v[62:65], v[174:177], v[218:221], v[62:65]
	v_mfma_f32_16x16x32_bf16 v[58:61], v[182:185], v[218:221], v[58:61]
	v_mfma_f32_16x16x32_bf16 v[46:49], v[174:177], v[226:229], v[46:49]
	v_mfma_f32_16x16x32_bf16 v[42:45], v[182:185], v[226:229], v[42:45]
	v_mfma_f32_16x16x32_bf16 v[30:33], v[174:177], v[234:237], v[30:33]
	v_mfma_f32_16x16x32_bf16 v[26:29], v[182:185], v[234:237], v[26:29]
	v_mfma_f32_16x16x32_bf16 v[14:17], v[174:177], v[242:245], v[14:17]
	v_mfma_f32_16x16x32_bf16 v[10:13], v[182:185], v[242:245], v[10:13]
	v_mfma_f32_16x16x32_bf16 v[54:57], v[186:189], v[214:217], v[54:57]
	v_mfma_f32_16x16x32_bf16 v[50:53], v[206:209], v[214:217], v[50:53]
	v_mfma_f32_16x16x32_bf16 v[38:41], v[186:189], v[222:225], v[38:41]
	v_mfma_f32_16x16x32_bf16 v[34:37], v[206:209], v[222:225], v[34:37]
	v_mfma_f32_16x16x32_bf16 v[22:25], v[186:189], v[230:233], v[22:25]
	v_mfma_f32_16x16x32_bf16 v[18:21], v[206:209], v[230:233], v[18:21]
	v_mfma_f32_16x16x32_bf16 v[6:9], v[186:189], v[238:241], v[6:9]
	v_mfma_f32_16x16x32_bf16 v[2:5], v[206:209], v[238:241], v[2:5]
	v_mfma_f32_16x16x32_bf16 v[54:57], v[190:193], v[218:221], v[54:57]
	v_mfma_f32_16x16x32_bf16 v[50:53], v[210:213], v[218:221], v[50:53]
	v_mfma_f32_16x16x32_bf16 v[38:41], v[190:193], v[226:229], v[38:41]
	v_mfma_f32_16x16x32_bf16 v[34:37], v[210:213], v[226:229], v[34:37]
	s_setprio 2
	v_mfma_f32_16x16x32_bf16 v[22:25], v[190:193], v[234:237], v[22:25]
	s_barrier
	v_mfma_f32_16x16x32_bf16 v[18:21], v[210:213], v[234:237], v[18:21]
	v_mfma_f32_16x16x32_bf16 v[6:9], v[190:193], v[242:245], v[6:9]
	v_mfma_f32_16x16x32_bf16 v[2:5], v[210:213], v[242:245], v[2:5]
	s_setprio 0
	s_add_i32 s50, s50, 2
	s_add_u32 s12, s12, 0x100
	s_addc_u32 s13, s13, 0
	s_cmp_gt_u32 s50, 13
	s_cbranch_scc1 .LBB0_211

; #define PG8_STAGE(bufoff, gbase, voff) do { _Pragma("unroll") for (int _i = 0; _i < 2; ++_i) \
;         __builtin_amdgcn_global_load_lds((const unsigned*)((const char*)(gbase) + (voff)[_i]), (PG8_LAS unsigned*)(lds + (bufoff) + ldsw + _i * 8192), 16, 0, 0); } while (0)
; #define PG8_LDA(dst, b, h) do { _Pragma("unroll") for (int m = 0; m < 4; ++m) _Pragma("unroll") for (int k = 0; k < 2; ++k) dst[m][k] = *(const PG8_LAS bf16x8*)(lds + PG8_SA(b, h) + aoff + m * 2048 + k * 1024); } while (0)
; #define PG8_LDB(dst, b, h) do { _Pragma("unroll") for (int n = 0; n < 2; ++n) _Pragma("unroll") for (int k = 0; k < 2; ++k) dst[n][k] = *(const PG8_LAS bf16x8*)(lds + PG8_SB(b, h) + boff + n * 2048 + k * 1024); } while (0)
; #define PG8_MMA(ai, bj, At, Bt) do { __builtin_amdgcn_s_setprio(1); _Pragma("unroll") for (int m = 0; m < 4; ++m) _Pragma("unroll") for (int n = 0; n < 2; ++n) _Pragma("unroll") for (int k = 0; k < 2; ++k) \
;         acc[ai][bj][m][n] = __builtin_amdgcn_mfma_f32_16x16x32_bf16(Bt[n][k], At[m][k], acc[ai][bj][m][n], 0, 0, 0); __builtin_amdgcn_s_setprio(0); } while (0)
; #define PG8_WAIT_V(n) asm volatile("s_waitcnt vmcnt(" #n ")" ::: "memory")
; #define PG8_WAIT_L(n) asm volatile("s_waitcnt lgkmcnt(" #n ")" ::: "memory")
; #define PG8_BAR __builtin_amdgcn_s_barrier()
; #define PG8_SCHED __builtin_amdgcn_sched_barrier(0)
; template <class Epi, class Sched, bool ALIGN_EPI = false, bool SP2 = false>
; __device__ __forceinline__ void gemm_phase(PG8_LAS unsigned char* lds, const Gemm g, const Sched& S, const Epi& E, const int tid) {
;     ...
;             PG8_LDB(B0, 0, 0); PG8_LDB(B1, 0, 1); PG8_SCHED; PG8_LDA(At, 0, 0); PG8_STAGE(PG8_SA(1, 1), a1 + hstep, voffA);
;             PG8_WAIT_V(8); PG8_WAIT_L(0); PG8_BAR; PG8_MMA(0, 0, At, B0); PG8_MMA(0, 1, At, B1); PG8_BAR; PG8_SCHED;
;             PG8_LDA(At, 0, 1); PG8_STAGE(PG8_SB(0, 0), b2, voffB); PG8_STAGE(PG8_SB(0, 1), b2 + hstep, voffB); PG8_STAGE(PG8_SA(0, 0), a2, voffA);
;             PG8_WAIT_V(8); PG8_WAIT_L(0); PG8_BAR; PG8_MMA(1, 0, At, B0); PG8_MMA(1, 1, At, B1); PG8_BAR; PG8_SCHED;
.LBB0_618:
	s_add_i32 s85, s70, 2
	s_add_u32 s38, s68, 0x80
	s_addc_u32 s39, s69, 0
	s_add_i32 s59, 0, 0x10000
	s_cmp_eq_u32 s81, s70
	s_cselect_b32 s71, s11, s39
	s_cselect_b32 s70, s10, s38
	s_cselect_b32 s39, s67, s51
	s_cselect_b32 s38, s66, s50
	s_add_i32 s86, 0, 0x14000
	ds_read_b128 v[130:133], v242
	ds_read_b128 v[134:137], v242 offset:1024
	ds_read_b128 v[138:141], v242 offset:2048
	ds_read_b128 v[142:145], v242 offset:3072
	ds_read_b128 v[146:149], v242 offset:16384
	ds_read_b128 v[150:153], v242 offset:17408
	ds_read_b128 v[176:179], v242 offset:18432
	ds_read_b128 v[180:183], v242 offset:19456
	s_add_i32 m0, s73, 0xc000
	ds_read_b128 v[184:187], v207
	ds_read_b128 v[188:191], v207 offset:1024
	ds_read_b128 v[208:211], v207 offset:2048
	ds_read_b128 v[212:215], v207 offset:3072
	ds_read_b128 v[216:219], v207 offset:4096
	ds_read_b128 v[220:223], v207 offset:5120
	ds_read_b128 v[224:227], v207 offset:6144
	ds_read_b128 v[228:231], v207 offset:7168
	global_load_lds_dwordx4 v172, s[68:69]
	s_add_i32 m0, s73, 0xe000
	s_nop 0
	global_load_lds_dwordx4 v174, s[68:69]
	s_waitcnt vmcnt(8)
	s_waitcnt lgkmcnt(0)
	s_setprio 1
	s_barrier
	v_mfma_f32_16x16x32_bf16 v[126:129], v[130:133], v[184:187], v[126:129]
	v_mfma_f32_16x16x32_bf16 v[122:125], v[138:141], v[184:187], v[122:125]
	v_mfma_f32_16x16x32_bf16 v[110:113], v[130:133], v[208:211], v[110:113]
	v_mfma_f32_16x16x32_bf16 v[106:109], v[138:141], v[208:211], v[106:109]
	v_mfma_f32_16x16x32_bf16 v[94:97], v[130:133], v[216:219], v[94:97]
	v_mfma_f32_16x16x32_bf16 v[90:93], v[138:141], v[216:219], v[90:93]
	v_mfma_f32_16x16x32_bf16 v[78:81], v[130:133], v[224:227], v[78:81]
	v_mfma_f32_16x16x32_bf16 v[74:77], v[138:141], v[224:227], v[74:77]
	v_mfma_f32_16x16x32_bf16 v[126:129], v[134:137], v[188:191], v[126:129]
	v_mfma_f32_16x16x32_bf16 v[122:125], v[142:145], v[188:191], v[122:125]
	v_mfma_f32_16x16x32_bf16 v[110:113], v[134:137], v[212:215], v[110:113]
	v_mfma_f32_16x16x32_bf16 v[106:109], v[142:145], v[212:215], v[106:109]
	v_mfma_f32_16x16x32_bf16 v[94:97], v[134:137], v[220:223], v[94:97]
	v_mfma_f32_16x16x32_bf16 v[90:93], v[142:145], v[220:223], v[90:93]
	v_mfma_f32_16x16x32_bf16 v[78:81], v[134:137], v[228:231], v[78:81]
	v_mfma_f32_16x16x32_bf16 v[74:77], v[142:145], v[228:231], v[74:77]
	v_mfma_f32_16x16x32_bf16 v[118:121], v[146:149], v[184:187], v[118:121]
	v_mfma_f32_16x16x32_bf16 v[114:117], v[176:179], v[184:187], v[114:117]
	v_mfma_f32_16x16x32_bf16 v[102:105], v[146:149], v[208:211], v[102:105]
	v_mfma_f32_16x16x32_bf16 v[98:101], v[176:179], v[208:211], v[98:101]
	v_mfma_f32_16x16x32_bf16 v[86:89], v[146:149], v[216:219], v[86:89]
	v_mfma_f32_16x16x32_bf16 v[82:85], v[176:179], v[216:219], v[82:85]
	v_mfma_f32_16x16x32_bf16 v[70:73], v[146:149], v[224:227], v[70:73]
	v_mfma_f32_16x16x32_bf16 v[66:69], v[176:179], v[224:227], v[66:69]
	v_mfma_f32_16x16x32_bf16 v[118:121], v[150:153], v[188:191], v[118:121]
	v_mfma_f32_16x16x32_bf16 v[114:117], v[180:183], v[188:191], v[114:117]
	v_mfma_f32_16x16x32_bf16 v[102:105], v[150:153], v[212:215], v[102:105]
	v_mfma_f32_16x16x32_bf16 v[98:101], v[180:183], v[212:215], v[98:101]
	s_setprio 2
	v_mfma_f32_16x16x32_bf16 v[86:89], v[150:153], v[220:223], v[86:89]
	s_barrier
	v_mfma_f32_16x16x32_bf16 v[82:85], v[180:183], v[220:223], v[82:85]
	v_mfma_f32_16x16x32_bf16 v[70:73], v[150:153], v[228:231], v[70:73]
	v_mfma_f32_16x16x32_bf16 v[66:69], v[180:183], v[228:231], v[66:69]
	s_setprio 0
	s_add_i32 s59, s59, s72
	s_mov_b64 s[90:91], s[38:39]
	s_mov_b32 m0, s59
	ds_read_b128 v[184:187], v207 offset:16384
	ds_read_b128 v[188:191], v207 offset:17408
	ds_read_b128 v[208:211], v207 offset:18432
	ds_read_b128 v[212:215], v207 offset:19456
	ds_read_b128 v[216:219], v207 offset:20480
	ds_read_b128 v[220:223], v207 offset:21504
	ds_read_b128 v[224:227], v207 offset:22528
	ds_read_b128 v[228:231], v207 offset:23552
	global_load_lds_dwordx4 v0, s[38:39]
	s_add_i32 m0, s59, 0x2000
	s_add_i32 s59, s86, s72
	global_load_lds_dwordx4 v166, s[38:39]
	s_add_u32 s38, s38, s14
	s_addc_u32 s39, s39, 0
	s_mov_b32 m0, s59
	s_nop 0
	global_load_lds_dwordx4 v0, s[38:39]
	s_add_i32 m0, s59, 0x2000
	s_nop 0
	global_load_lds_dwordx4 v166, s[38:39]
	s_mov_b32 m0, s73
	s_nop 0
	global_load_lds_dwordx4 v170, s[70:71]
	s_mov_b32 m0, s74
	s_nop 0
	global_load_lds_dwordx4 v168, s[70:71]
	s_waitcnt vmcnt(8)
	s_waitcnt lgkmcnt(0)
	s_setprio 1
	s_barrier
	v_mfma_f32_16x16x32_bf16 v[62:65], v[130:133], v[184:187], v[62:65]
	v_mfma_f32_16x16x32_bf16 v[58:61], v[138:141], v[184:187], v[58:61]
	v_mfma_f32_16x16x32_bf16 v[46:49], v[130:133], v[208:211], v[46:49]
	v_mfma_f32_16x16x32_bf16 v[42:45], v[138:141], v[208:211], v[42:45]
	v_mfma_f32_16x16x32_bf16 v[30:33], v[130:133], v[216:219], v[30:33]
	v_mfma_f32_16x16x32_bf16 v[26:29], v[138:141], v[216:219], v[26:29]
	v_mfma_f32_16x16x32_bf16 v[14:17], v[130:133], v[224:227], v[14:17]
	v_mfma_f32_16x16x32_bf16 v[10:13], v[138:141], v[224:227], v[10:13]
	v_mfma_f32_16x16x32_bf16 v[62:65], v[134:137], v[188:191], v[62:65]
	v_mfma_f32_16x16x32_bf16 v[58:61], v[142:145], v[188:191], v[58:61]
	v_mfma_f32_16x16x32_bf16 v[46:49], v[134:137], v[212:215], v[46:49]
	v_mfma_f32_16x16x32_bf16 v[42:45], v[142:145], v[212:215], v[42:45]
	v_mfma_f32_16x16x32_bf16 v[30:33], v[134:137], v[220:223], v[30:33]
	v_mfma_f32_16x16x32_bf16 v[26:29], v[142:145], v[220:223], v[26:29]
	v_mfma_f32_16x16x32_bf16 v[14:17], v[134:137], v[228:231], v[14:17]
	v_mfma_f32_16x16x32_bf16 v[10:13], v[142:145], v[228:231], v[10:13]
	v_mfma_f32_16x16x32_bf16 v[54:57], v[146:149], v[184:187], v[54:57]
	v_mfma_f32_16x16x32_bf16 v[50:53], v[176:179], v[184:187], v[50:53]
	v_mfma_f32_16x16x32_bf16 v[38:41], v[146:149], v[208:211], v[38:41]
	v_mfma_f32_16x16x32_bf16 v[34:37], v[176:179], v[208:211], v[34:37]
	v_mfma_f32_16x16x32_bf16 v[22:25], v[146:149], v[216:219], v[22:25]
	v_mfma_f32_16x16x32_bf16 v[18:21], v[176:179], v[216:219], v[18:21]
	v_mfma_f32_16x16x32_bf16 v[6:9], v[146:149], v[224:227], v[6:9]
	v_mfma_f32_16x16x32_bf16 v[2:5], v[176:179], v[224:227], v[2:5]
	v_mfma_f32_16x16x32_bf16 v[54:57], v[150:153], v[188:191], v[54:57]
	v_mfma_f32_16x16x32_bf16 v[50:53], v[180:183], v[188:191], v[50:53]
	v_mfma_f32_16x16x32_bf16 v[38:41], v[150:153], v[212:215], v[38:41]
	v_mfma_f32_16x16x32_bf16 v[34:37], v[180:183], v[212:215], v[34:37]
	s_setprio 2
	v_mfma_f32_16x16x32_bf16 v[22:25], v[150:153], v[220:223], v[22:25]
	s_barrier
; #define PG8_STAGE(bufoff, gbase, voff) do { _Pragma("unroll") for (int _i = 0; _i < 2; ++_i) \
;         __builtin_amdgcn_global_load_lds((const unsigned*)((const char*)(gbase) + (voff)[_i]), (PG8_LAS unsigned*)(lds + (bufoff) + ldsw + _i * 8192), 16, 0, 0); } while (0)
; #define PG8_LDA(dst, b, h) do { _Pragma("unroll") for (int m = 0; m < 4; ++m) _Pragma("unroll") for (int k = 0; k < 2; ++k) dst[m][k] = *(const PG8_LAS bf16x8*)(lds + PG8_SA(b, h) + aoff + m * 2048 + k * 1024); } while (0)
; #define PG8_LDB(dst, b, h) do { _Pragma("unroll") for (int n = 0; n < 2; ++n) _Pragma("unroll") for (int k = 0; k < 2; ++k) dst[n][k] = *(const PG8_LAS bf16x8*)(lds + PG8_SB(b, h) + boff + n * 2048 + k * 1024); } while (0)
; #define PG8_MMA(ai, bj, At, Bt) do { __builtin_amdgcn_s_setprio(1); _Pragma("unroll") for (int m = 0; m < 4; ++m) _Pragma("unroll") for (int n = 0; n < 2; ++n) _Pragma("unroll") for (int k = 0; k < 2; ++k) \
;         acc[ai][bj][m][n] = __builtin_amdgcn_mfma_f32_16x16x32_bf16(Bt[n][k], At[m][k], acc[ai][bj][m][n], 0, 0, 0); __builtin_amdgcn_s_setprio(0); } while (0)
; #define PG8_WAIT_V(n) asm volatile("s_waitcnt vmcnt(" #n ")" ::: "memory")
; #define PG8_WAIT_L(n) asm volatile("s_waitcnt lgkmcnt(" #n ")" ::: "memory")
; #define PG8_BAR __builtin_amdgcn_s_barrier()
; #define PG8_SCHED __builtin_amdgcn_sched_barrier(0)
; template <class Epi, class Sched, bool ALIGN_EPI = false, bool SP2 = false>
; __device__ __forceinline__ void gemm_phase(PG8_LAS unsigned char* lds, const Gemm g, const Sched& S, const Epi& E, const int tid) {
;     ...
;             PG8_WAIT_V(8); PG8_WAIT_L(0); PG8_BAR; PG8_MMA(1, 0, At, B0); PG8_MMA(1, 1, At, B1); PG8_BAR; PG8_SCHED;
;             PG8_LDB(B0, 1, 0); PG8_LDB(B1, 1, 1); PG8_SCHED; PG8_LDA(At, 1, 0); PG8_STAGE(PG8_SA(0, 1), a2 + hstep, voffA);
;             PG8_WAIT_V(8); PG8_WAIT_L(0); PG8_BAR; PG8_MMA(0, 0, At, B0); PG8_MMA(0, 1, At, B1); PG8_BAR; PG8_SCHED;
;             PG8_LDA(At, 1, 1); PG8_STAGE(PG8_SB(1, 0), b3, voffB); PG8_STAGE(PG8_SB(1, 1), b3 + hstep, voffB); PG8_STAGE(PG8_SA(1, 0), a3, voffA);
;             PG8_WAIT_V(8); PG8_WAIT_L(0); PG8_BAR; PG8_MMA(1, 0, At, B0); PG8_MMA(1, 1, At, B1); PG8_BAR; PG8_SCHED;
	v_mfma_f32_16x16x32_bf16 v[18:21], v[180:183], v[220:223], v[18:21]
	v_mfma_f32_16x16x32_bf16 v[6:9], v[150:153], v[228:231], v[6:9]
	v_mfma_f32_16x16x32_bf16 v[2:5], v[180:183], v[228:231], v[2:5]
	s_setprio 0
	s_add_i32 s59, 0, 0x18000
	s_add_i32 s86, 0, 0x1c000
	ds_read_b128 v[130:133], v242 offset:32768
	ds_read_b128 v[134:137], v242 offset:33792
	ds_read_b128 v[138:141], v242 offset:34816
	ds_read_b128 v[142:145], v242 offset:35840
	ds_read_b128 v[146:149], v242 offset:49152
	ds_read_b128 v[150:153], v242 offset:50176
	ds_read_b128 v[176:179], v242 offset:51200
	ds_read_b128 v[180:183], v242 offset:52224
	s_add_u32 s38, s70, s14
	s_addc_u32 s39, s71, 0
	s_mov_b32 m0, s75
	ds_read_b128 v[184:187], v207 offset:32768
	ds_read_b128 v[188:191], v207 offset:33792
	ds_read_b128 v[208:211], v207 offset:34816
	ds_read_b128 v[212:215], v207 offset:35840
	ds_read_b128 v[216:219], v207 offset:36864
	ds_read_b128 v[220:223], v207 offset:37888
	ds_read_b128 v[224:227], v207 offset:38912
	ds_read_b128 v[228:231], v207 offset:39936
	global_load_lds_dwordx4 v170, s[38:39]
	s_mov_b32 m0, s76
	s_nop 0
	global_load_lds_dwordx4 v168, s[38:39]
	s_waitcnt vmcnt(8)
	s_waitcnt lgkmcnt(0)
	s_setprio 1
	s_barrier
	v_mfma_f32_16x16x32_bf16 v[126:129], v[130:133], v[184:187], v[126:129]
	v_mfma_f32_16x16x32_bf16 v[122:125], v[138:141], v[184:187], v[122:125]
	v_mfma_f32_16x16x32_bf16 v[110:113], v[130:133], v[208:211], v[110:113]
	v_mfma_f32_16x16x32_bf16 v[106:109], v[138:141], v[208:211], v[106:109]
	v_mfma_f32_16x16x32_bf16 v[94:97], v[130:133], v[216:219], v[94:97]
	v_mfma_f32_16x16x32_bf16 v[90:93], v[138:141], v[216:219], v[90:93]
	v_mfma_f32_16x16x32_bf16 v[78:81], v[130:133], v[224:227], v[78:81]
	v_mfma_f32_16x16x32_bf16 v[74:77], v[138:141], v[224:227], v[74:77]
	v_mfma_f32_16x16x32_bf16 v[126:129], v[134:137], v[188:191], v[126:129]
	v_mfma_f32_16x16x32_bf16 v[122:125], v[142:145], v[188:191], v[122:125]
	v_mfma_f32_16x16x32_bf16 v[110:113], v[134:137], v[212:215], v[110:113]
	v_mfma_f32_16x16x32_bf16 v[106:109], v[142:145], v[212:215], v[106:109]
	v_mfma_f32_16x16x32_bf16 v[94:97], v[134:137], v[220:223], v[94:97]
	v_mfma_f32_16x16x32_bf16 v[90:93], v[142:145], v[220:223], v[90:93]
	v_mfma_f32_16x16x32_bf16 v[78:81], v[134:137], v[228:231], v[78:81]
	v_mfma_f32_16x16x32_bf16 v[74:77], v[142:145], v[228:231], v[74:77]
	v_mfma_f32_16x16x32_bf16 v[118:121], v[146:149], v[184:187], v[118:121]
	v_mfma_f32_16x16x32_bf16 v[114:117], v[176:179], v[184:187], v[114:117]
	v_mfma_f32_16x16x32_bf16 v[102:105], v[146:149], v[208:211], v[102:105]
	v_mfma_f32_16x16x32_bf16 v[98:101], v[176:179], v[208:211], v[98:101]
	v_mfma_f32_16x16x32_bf16 v[86:89], v[146:149], v[216:219], v[86:89]
	v_mfma_f32_16x16x32_bf16 v[82:85], v[176:179], v[216:219], v[82:85]
	v_mfma_f32_16x16x32_bf16 v[70:73], v[146:149], v[224:227], v[70:73]
	v_mfma_f32_16x16x32_bf16 v[66:69], v[176:179], v[224:227], v[66:69]
	v_mfma_f32_16x16x32_bf16 v[118:121], v[150:153], v[188:191], v[118:121]
	v_mfma_f32_16x16x32_bf16 v[114:117], v[180:183], v[188:191], v[114:117]
	v_mfma_f32_16x16x32_bf16 v[102:105], v[150:153], v[212:215], v[102:105]
	v_mfma_f32_16x16x32_bf16 v[98:101], v[180:183], v[212:215], v[98:101]
	s_setprio 2
	v_mfma_f32_16x16x32_bf16 v[86:89], v[150:153], v[220:223], v[86:89]
	s_barrier
	v_mfma_f32_16x16x32_bf16 v[82:85], v[180:183], v[220:223], v[82:85]
	v_mfma_f32_16x16x32_bf16 v[70:73], v[150:153], v[228:231], v[70:73]
	v_mfma_f32_16x16x32_bf16 v[66:69], v[180:183], v[228:231], v[66:69]
	s_setprio 0
	s_add_i32 s38, s59, s72
	s_add_u32 s90, s90, 0x80
	s_addc_u32 s91, s91, 0
	s_mov_b32 m0, s38
	ds_read_b128 v[184:187], v207 offset:49152
	ds_read_b128 v[188:191], v207 offset:50176
	ds_read_b128 v[208:211], v207 offset:51200
	ds_read_b128 v[212:215], v207 offset:52224
	ds_read_b128 v[216:219], v207 offset:53248
	ds_read_b128 v[220:223], v207 offset:54272
	ds_read_b128 v[224:227], v207 offset:55296
	ds_read_b128 v[228:231], v207 offset:56320
	global_load_lds_dwordx4 v0, s[90:91]
	s_add_i32 m0, s38, 0x2000
	s_add_i32 s38, s86, s72
	global_load_lds_dwordx4 v166, s[90:91]
	s_add_u32 s90, s90, s14
	s_addc_u32 s91, s91, 0
	s_mov_b32 m0, s38
	s_nop 0
	global_load_lds_dwordx4 v0, s[90:91]
	s_add_i32 m0, s38, 0x2000
	s_add_u32 s92, s70, 0x80
	s_addc_u32 s93, s71, 0
	global_load_lds_dwordx4 v166, s[90:91]
	s_mov_b32 m0, s79
	s_nop 0
	global_load_lds_dwordx4 v170, s[92:93]
	s_mov_b32 m0, s80
	s_nop 0
	global_load_lds_dwordx4 v168, s[92:93]
	s_waitcnt vmcnt(8)
	s_waitcnt lgkmcnt(0)
	s_setprio 1
	s_barrier
	v_mfma_f32_16x16x32_bf16 v[62:65], v[130:133], v[184:187], v[62:65]
	v_mfma_f32_16x16x32_bf16 v[58:61], v[138:141], v[184:187], v[58:61]
	v_mfma_f32_16x16x32_bf16 v[46:49], v[130:133], v[208:211], v[46:49]
	v_mfma_f32_16x16x32_bf16 v[42:45], v[138:141], v[208:211], v[42:45]
	v_mfma_f32_16x16x32_bf16 v[30:33], v[130:133], v[216:219], v[30:33]
	v_mfma_f32_16x16x32_bf16 v[26:29], v[138:141], v[216:219], v[26:29]
	v_mfma_f32_16x16x32_bf16 v[14:17], v[130:133], v[224:227], v[14:17]
	v_mfma_f32_16x16x32_bf16 v[10:13], v[138:141], v[224:227], v[10:13]
	v_mfma_f32_16x16x32_bf16 v[62:65], v[134:137], v[188:191], v[62:65]
	v_mfma_f32_16x16x32_bf16 v[58:61], v[142:145], v[188:191], v[58:61]
	v_mfma_f32_16x16x32_bf16 v[46:49], v[134:137], v[212:215], v[46:49]
	v_mfma_f32_16x16x32_bf16 v[42:45], v[142:145], v[212:215], v[42:45]
	v_mfma_f32_16x16x32_bf16 v[30:33], v[134:137], v[220:223], v[30:33]
	v_mfma_f32_16x16x32_bf16 v[26:29], v[142:145], v[220:223], v[26:29]
	v_mfma_f32_16x16x32_bf16 v[14:17], v[134:137], v[228:231], v[14:17]
	v_mfma_f32_16x16x32_bf16 v[10:13], v[142:145], v[228:231], v[10:13]
	v_mfma_f32_16x16x32_bf16 v[54:57], v[146:149], v[184:187], v[54:57]
	v_mfma_f32_16x16x32_bf16 v[50:53], v[176:179], v[184:187], v[50:53]
	v_mfma_f32_16x16x32_bf16 v[38:41], v[146:149], v[208:211], v[38:41]
	v_mfma_f32_16x16x32_bf16 v[34:37], v[176:179], v[208:211], v[34:37]
	v_mfma_f32_16x16x32_bf16 v[22:25], v[146:149], v[216:219], v[22:25]
	v_mfma_f32_16x16x32_bf16 v[18:21], v[176:179], v[216:219], v[18:21]
	v_mfma_f32_16x16x32_bf16 v[6:9], v[146:149], v[224:227], v[6:9]
	v_mfma_f32_16x16x32_bf16 v[2:5], v[176:179], v[224:227], v[2:5]
	v_mfma_f32_16x16x32_bf16 v[54:57], v[150:153], v[188:191], v[54:57]
	v_mfma_f32_16x16x32_bf16 v[50:53], v[180:183], v[188:191], v[50:53]
	v_mfma_f32_16x16x32_bf16 v[38:41], v[150:153], v[212:215], v[38:41]
	v_mfma_f32_16x16x32_bf16 v[34:37], v[180:183], v[212:215], v[34:37]
	s_setprio 2
	v_mfma_f32_16x16x32_bf16 v[22:25], v[150:153], v[220:223], v[22:25]
	s_barrier
	v_mfma_f32_16x16x32_bf16 v[18:21], v[180:183], v[220:223], v[18:21]
	v_mfma_f32_16x16x32_bf16 v[6:9], v[150:153], v[228:231], v[6:9]
	v_mfma_f32_16x16x32_bf16 v[2:5], v[180:183], v[228:231], v[2:5]
	s_setprio 0
	s_add_u32 s68, s68, 0x100
	s_addc_u32 s69, s69, 0
	s_add_u32 s50, s50, 0x100
	s_addc_u32 s51, s51, 0
	s_cmp_ge_u32 s85, s78
	s_mov_b32 s70, s85
	s_cbranch_scc0 .LBB0_618
	s_and_b64 vcc, exec, s[22:23]
	s_cbranch_vccz .LBB0_621
	s_barrier
